# fp8 FFN down-projection operands (hidden activations + weight images) stored in a bank-conflict-free LDS sub-tile layout; same math
# speedup vs baseline: 1.0102x; 1.0102x over previous
; #define LAS __attribute__((address_space(3)))
; #define GAS __attribute__((address_space(1)))
; #define LDS_WAIT() asm volatile("s_waitcnt lgkmcnt(0)" ::: "memory")
; __device__ __forceinline__ void transpose_item(LAS unsigned char* lds, const TItem& it, int wv) {
;     ...
; #pragma unroll
;         for (int i = 0; i < 8; ++i)
; #pragma unroll
;             for (int j = 0; j < 4; ++j) scr[(kk + 8 * i) * 33 + 4 * q + j] = w[i][j] * cs[j];
;         LDS_WAIT();
;         if (it.f8) {
;             GAS char* dk8 = (GAS char*)it.dst + (size_t)(it.row0 >> 7) * (it.K >> 7) * pg8::HTB + (size_t)(((it.row0 & 127) >> 4) * 2048) + lane * 16 + (size_t)(k0 >> 7) * pg8::HTB + ((k0 >> 6) & 1) * 1024;
; #pragma unroll
;             for (int rbh = 0; rbh < 2; ++rbh) {
;                 const int c32 = pg8::perm32(16 * rbh + rr);
;                 const LAS float* s = scr + (16 * qc) * 33 + c32;
;                 u32x4 o;
.LBB0_149:
	s_lshl_b32 s4, s79, 8
	s_mul_hi_u32 s5, s4, s50
	s_mul_i32 s4, s4, s50
	s_add_u32 s4, s26, s4
	s_addc_u32 s5, s27, s5
	s_add_u32 s4, s4, s49
	s_addc_u32 s5, s5, 0
	v_lshl_add_u64 v[52:53], s[4:5], 0, v[144:145]
	s_lshl_b64 s[4:5], s[36:37], 2
	s_add_u32 s4, s40, s4
	s_addc_u32 s5, s41, s5
	v_lshl_add_u64 v[54:55], v[0:1], 2, s[4:5]
	s_add_u32 s4, s26, s49
	s_addc_u32 s5, s27, 0
	s_cmp_lg_u32 s6, 0
	v_lshl_add_u64 v[0:1], s[4:5], 0, v[144:145]
	s_cselect_b64 s[4:5], -1, 0
	s_lshr_b32 s6, s79, 7
	s_lshl_b32 s37, s50, 14
	v_mov_b32_e32 v6, s6
	v_lshlrev_b32_e32 v3, 3, v157
	v_mad_u64_u32 v[56:57], s[46:47], s37, v6, v[0:1]
	s_lshr_b32 s37, s50, 18
	v_and_b32_e32 v3, 0x60, v3
	v_and_b32_e32 v4, 12, v155
	s_mul_i32 s37, s37, s6
	s_mul_i32 s6, s9, s81
	v_add3_u32 v3, s51, v3, v4
	v_lshrrev_b32_e32 v4, 1, v16
	v_add_u32_e32 v57, s37, v57
	s_lshl_b32 s37, s6, 4
	s_lshl_b32 s6, s6, 2
	v_lshl_add_u32 v2, v147, 4, s51
	v_mul_u32_u24_e32 v5, 0x84, v156
	v_mul_u32_u24_e32 v4, 0x84, v4
	s_add_i32 s6, s6, 0
	v_mov_b32_e32 v12, v145
	v_mov_b32_e32 v13, v145
	v_mad_u32_u24 v58, v158, s76, v3
	v_and_b32_e32 v180, 1, v155
	v_mul_u32_u24_e32 v180, 0x1080, v180
	v_sub_u32_e32 v180, 0x840, v180
	v_and_b32_e32 v181, 32, v155
	v_cmp_ne_u32_e32 vcc, 0, v181
	s_and_b64 vcc, vcc, s[44:45]
	s_nop 1
	v_cndmask_b32_e32 v180, 0, v180, vcc
	v_add_u32_e32 v58, v58, v180
	s_add_i32 s6, s6, 0x10800
	v_mov_b32_e32 v14, v145
	v_mov_b32_e32 v15, v145
	v_add_u32_e32 v60, v2, v5
	v_add_u32_e32 v61, v3, v4
	v_mov_b64_e32 v[8:9], v[12:13]
	v_mov_b64_e32 v[4:5], v[12:13]
	v_mov_b64_e32 v[0:1], v[12:13]
	v_lshl_add_u32 v59, v156, 2, s6
	s_mov_b32 s81, s48
	v_mov_b64_e32 v[10:11], v[14:15]
	v_mov_b64_e32 v[6:7], v[14:15]
	v_mov_b64_e32 v[2:3], v[14:15]
	s_branch .LBB0_151

.LBB0_331:
	s_andn2_b64 vcc, exec, s[28:29]
	s_ashr_i32 s27, s26, 31
	s_cbranch_vccnz .LBB0_333
	global_load_dwordx4 v[50:53], v[182:183], off offset:16
	global_load_dwordx4 v[68:71], v[182:183], off
	global_load_dwordx4 v[54:57], v[182:183], off offset:528
	global_load_dwordx4 v[74:77], v[182:183], off offset:512
	global_load_dwordx4 v[58:61], v[180:181], off offset:16
	global_load_dwordx4 v[78:81], v[180:181], off
	global_load_dwordx4 v[62:65], v[180:181], off offset:528
	global_load_dwordx4 v[190:193], v[180:181], off offset:512
	s_add_u32 s14, s31, s26
	s_addc_u32 s15, s30, s27
	s_lshl_b64 s[14:15], s[14:15], 14
	v_readlane_b32 s16, v255, 26
	s_add_u32 s28, s16, s14
	v_readlane_b32 s14, v255, 28
	s_addc_u32 s29, s14, s15
	v_readlane_b32 s14, v255, 30
	s_mov_b32 s16, 0x3fb8aa3b
	s_mov_b32 s20, 0xc0317218
	v_or_b32_e32 v0, s14, v217
	s_mov_b32 s14, 0xbfb8aa3b
	v_add_u32_e32 v0, v0, v184
	v_xor_b32_e32 v0, v0, v185
	v_lshrrev_b32_e32 v185, 1, v185
	v_xor_b32_e32 v0, v0, v185
	s_mov_b32 s22, 0x40317218
	s_waitcnt lgkmcnt(0)
	v_pk_mul_f32 v[82:83], v[138:139], v[172:173] op_sel_hi:[0,1]
	v_pk_mul_f32 v[158:159], v[136:137], v[158:159] op_sel_hi:[0,1]
	v_pk_mul_f32 v[142:143], v[134:135], v[142:143] op_sel_hi:[0,1]
	v_pk_mul_f32 v[114:115], v[132:133], v[114:115] op_sel_hi:[0,1]
	v_pk_mul_f32 v[118:119], v[132:133], v[118:119] op_sel_hi:[0,1]
	v_pk_mul_f32 v[116:117], v[132:133], v[116:117] op_sel_hi:[0,1]
	v_pk_mul_f32 v[98:99], v[138:139], v[98:99] op_sel_hi:[0,1]
	v_pk_mul_f32 v[92:93], v[138:139], v[92:93] op_sel_hi:[0,1]
	v_cvt_f32_i32_e32 v47, v47
	v_cvt_f32_i32_e32 v46, v46
	v_lshl_add_u64 v[66:67], s[28:29], 0, v[0:1]
	v_cvt_f32_i32_e32 v49, v49
	v_cvt_f32_i32_e32 v48, v48
	v_pk_mul_f32 v[46:47], v[136:137], v[46:47] op_sel_hi:[0,1]
	v_cvt_f32_i32_e32 v43, v43
	v_cvt_f32_i32_e32 v42, v42
	v_pk_mul_f32 v[48:49], v[136:137], v[48:49] op_sel_hi:[0,1]
	v_cvt_f32_i32_e32 v45, v45
	v_cvt_f32_i32_e32 v44, v44
	v_pk_mul_f32 v[42:43], v[136:137], v[42:43] op_sel_hi:[0,1]
	v_cvt_f32_i32_e32 v39, v39
	v_cvt_f32_i32_e32 v38, v38
	v_pk_mul_f32 v[44:45], v[136:137], v[44:45] op_sel_hi:[0,1]
	v_cvt_f32_i32_e32 v41, v41
	v_cvt_f32_i32_e32 v40, v40
	v_cvt_f32_i32_e32 v35, v35
	v_cvt_f32_i32_e32 v34, v34
	v_cvt_f32_i32_e32 v37, v37
	v_cvt_f32_i32_e32 v36, v36
	v_cvt_f32_i32_e32 v31, v31
	v_cvt_f32_i32_e32 v30, v30
	v_cvt_f32_i32_e32 v33, v33
	v_cvt_f32_i32_e32 v32, v32
	v_cvt_f32_i32_e32 v27, v27
	v_pk_mul_f32 v[30:31], v[134:135], v[30:31] op_sel_hi:[0,1]
	v_cvt_f32_i32_e32 v26, v26
	v_pk_mul_f32 v[32:33], v[134:135], v[32:33] op_sel_hi:[0,1]
	v_cvt_f32_i32_e32 v29, v29
	v_cvt_f32_i32_e32 v28, v28
	v_pk_mul_f32 v[26:27], v[134:135], v[26:27] op_sel_hi:[0,1]
	v_cvt_f32_i32_e32 v23, v23
	v_cvt_f32_i32_e32 v22, v22
	v_pk_mul_f32 v[28:29], v[134:135], v[28:29] op_sel_hi:[0,1]
	v_cvt_f32_i32_e32 v25, v25
	v_cvt_f32_i32_e32 v24, v24
	v_cvt_f32_i32_e32 v19, v19
	v_cvt_f32_i32_e32 v18, v18
	v_cvt_f32_i32_e32 v21, v21
	v_cvt_f32_i32_e32 v20, v20
	v_cvt_f32_i32_e32 v15, v15
	v_cvt_f32_i32_e32 v14, v14
	v_cvt_f32_i32_e32 v17, v17
	v_cvt_f32_i32_e32 v16, v16
	v_cvt_f32_i32_e32 v11, v11
	v_pk_mul_f32 v[14:15], v[132:133], v[14:15] op_sel_hi:[0,1]
	v_cvt_f32_i32_e32 v10, v10
	v_pk_mul_f32 v[16:17], v[132:133], v[16:17] op_sel_hi:[0,1]
	v_cvt_f32_i32_e32 v13, v13
	s_waitcnt vmcnt(0)
	v_pk_mul_f32 v[96:97], v[68:69], s[14:15] op_sel_hi:[1,0]
	v_pk_mul_f32 v[68:69], v[138:139], v[178:179] op_sel_hi:[0,1]
	v_pk_mul_f32 v[182:183], v[70:71], s[14:15] op_sel_hi:[1,0]
	v_pk_mul_f32 v[70:71], v[138:139], v[174:175] op_sel_hi:[0,1]
	v_pk_mul_f32 v[180:181], v[78:79], s[16:17] op_sel_hi:[1,0]
	v_pk_mul_f32 v[184:185], v[80:81], s[16:17] op_sel_hi:[1,0]
	v_pk_fma_f32 v[68:69], v[68:69], v[180:181], v[96:97] neg_lo:[1,0,0] neg_hi:[1,0,0]
	v_pk_fma_f32 v[70:71], v[70:71], v[184:185], v[182:183] neg_lo:[1,0,0] neg_hi:[1,0,0]
	v_exp_f32_e32 v94, v68
	v_exp_f32_e32 v95, v69
	v_exp_f32_e32 v104, v70
	v_exp_f32_e32 v105, v71
	v_add_f32_e32 v94, 1.0, v94
	v_add_f32_e32 v95, 1.0, v95
	v_rcp_f32_e32 v94, v94
	v_rcp_f32_e32 v95, v95
	v_add_f32_e32 v104, 1.0, v104
	v_add_f32_e32 v105, 1.0, v105
	v_rcp_f32_e32 v104, v104
	v_rcp_f32_e32 v105, v105
	v_pk_mul_f32 v[74:75], v[74:75], s[20:21] op_sel_hi:[1,0]
	v_pk_mul_f32 v[78:79], v[190:191], s[22:23] op_sel_hi:[1,0]
	v_pk_mul_f32 v[80:81], v[138:139], v[176:177] op_sel_hi:[0,1]
	v_pk_mul_f32 v[72:73], v[76:77], s[20:21] op_sel_hi:[1,0]
	v_pk_mul_f32 v[76:77], v[192:193], s[22:23] op_sel_hi:[1,0]
	v_pk_fma_f32 v[80:81], v[80:81], v[78:79], v[74:75] neg_lo:[1,0,0] neg_hi:[1,0,0]
	v_pk_mul_f32 v[68:69], v[68:69], v[94:95]
	v_pk_fma_f32 v[82:83], v[82:83], v[76:77], v[72:73] neg_lo:[1,0,0] neg_hi:[1,0,0]
	v_pk_mul_f32 v[70:71], v[70:71], v[104:105]
	v_pk_mul_f32 v[68:69], v[80:81], v[68:69]
	s_mov_b32 s15, 0xc3e00000
	v_pk_mul_f32 v[70:71], v[82:83], v[70:71]
	v_med3_f32 v68, v68, s15, v209
	v_med3_f32 v69, v69, s15, v209
	v_mov_b32_e32 v82, v1
	v_cvt_pk_fp8_f32 v82, v68, v69
	v_med3_f32 v70, v70, s15, v209
	v_med3_f32 v71, v71, s15, v209
	v_pk_fma_f32 v[142:143], v[142:143], v[76:77], v[72:73] neg_lo:[1,0,0] neg_hi:[1,0,0]
	v_cvt_pk_fp8_f32 v82, v70, v71 op_sel:[0,0,1]
	v_mov_b32_e32 v70, v139
	v_pk_mul_f32 v[68:69], v[70:71], v[168:169] op_sel_hi:[0,1]
	v_pk_fma_f32 v[68:69], v[68:69], v[180:181], v[96:97] neg_lo:[1,0,0] neg_hi:[1,0,0]
	v_pk_mul_f32 v[80:81], v[70:71], v[164:165] op_sel_hi:[0,1]
	v_pk_mul_f32 v[94:95], v[70:71], v[170:171] op_sel_hi:[0,1]
	v_pk_mul_f32 v[104:105], v[70:71], v[166:167] op_sel_hi:[0,1]
	v_exp_f32_e32 v71, v68
	v_pk_fma_f32 v[80:81], v[80:81], v[184:185], v[182:183] neg_lo:[1,0,0] neg_hi:[1,0,0]
	v_pk_fma_f32 v[94:95], v[94:95], v[78:79], v[74:75] neg_lo:[1,0,0] neg_hi:[1,0,0]
	v_pk_fma_f32 v[104:105], v[104:105], v[76:77], v[72:73] neg_lo:[1,0,0] neg_hi:[1,0,0]
	v_add_f32_e32 v71, 1.0, v71
	v_rcp_f32_e32 v164, v71
	v_exp_f32_e32 v71, v69
	v_pk_fma_f32 v[114:115], v[114:115], v[184:185], v[182:183] neg_lo:[1,0,0] neg_hi:[1,0,0]
	v_pk_fma_f32 v[116:117], v[116:117], v[76:77], v[72:73] neg_lo:[1,0,0] neg_hi:[1,0,0]
	v_pk_fma_f32 v[118:119], v[118:119], v[78:79], v[74:75] neg_lo:[1,0,0] neg_hi:[1,0,0]
	v_add_f32_e32 v71, 1.0, v71
	v_rcp_f32_e32 v165, v71
	v_exp_f32_e32 v71, v80
	v_pk_mul_f32 v[50:51], v[50:51], s[14:15] op_sel_hi:[1,0]
	v_pk_mul_f32 v[52:53], v[52:53], s[14:15] op_sel_hi:[1,0]
	v_pk_mul_f32 v[68:69], v[68:69], v[164:165]
	v_add_f32_e32 v71, 1.0, v71
	v_rcp_f32_e32 v166, v71
	v_exp_f32_e32 v71, v81
	v_pk_mul_f32 v[68:69], v[94:95], v[68:69]
	v_mov_b32_e32 v94, v1
	v_med3_f32 v68, v68, s15, v209
	v_add_f32_e32 v71, 1.0, v71
	v_rcp_f32_e32 v167, v71
	v_med3_f32 v69, v69, s15, v209
	v_cvt_pk_fp8_f32 v94, v68, v69
	v_pk_mul_f32 v[68:69], v[136:137], v[160:161] op_sel_hi:[0,1]
	v_pk_mul_f32 v[80:81], v[80:81], v[166:167]
	v_pk_fma_f32 v[68:69], v[68:69], v[78:79], v[74:75] neg_lo:[1,0,0] neg_hi:[1,0,0]
	v_pk_mul_f32 v[80:81], v[104:105], v[80:81]
	v_pk_mul_f32 v[104:105], v[136:137], v[162:163] op_sel_hi:[0,1]
	v_med3_f32 v71, v80, s15, v209
	v_med3_f32 v80, v81, s15, v209
	v_pk_fma_f32 v[104:105], v[104:105], v[180:181], v[96:97] neg_lo:[1,0,0] neg_hi:[1,0,0]
	v_cvt_pk_fp8_f32 v94, v71, v80 op_sel:[0,0,1]
	v_exp_f32_e32 v71, v104
	v_pk_mul_f32 v[80:81], v[136:137], v[156:157] op_sel_hi:[0,1]
	v_pk_fma_f32 v[156:157], v[158:159], v[184:185], v[182:183] neg_lo:[1,0,0] neg_hi:[1,0,0]
	v_pk_fma_f32 v[80:81], v[80:81], v[76:77], v[72:73] neg_lo:[1,0,0] neg_hi:[1,0,0]
	v_add_f32_e32 v71, 1.0, v71
	v_rcp_f32_e32 v158, v71
	v_exp_f32_e32 v71, v105
	v_mov_b32_e32 v95, v1
	v_cvt_f32_i32_e32 v12, v12
	v_pk_mul_f32 v[10:11], v[132:133], v[10:11] op_sel_hi:[0,1]
	v_add_f32_e32 v71, 1.0, v71
	v_rcp_f32_e32 v159, v71
	v_exp_f32_e32 v71, v156
	v_cvt_f32_i32_e32 v3, v3
	v_cvt_f32_i32_e32 v2, v2
	v_pk_mul_f32 v[104:105], v[104:105], v[158:159]
	v_add_f32_e32 v71, 1.0, v71
	v_rcp_f32_e32 v160, v71
	v_exp_f32_e32 v71, v157
	v_pk_mul_f32 v[68:69], v[68:69], v[104:105]
	v_mov_b32_e32 v158, v1
	v_med3_f32 v68, v68, s15, v209
	v_add_f32_e32 v71, 1.0, v71
	v_rcp_f32_e32 v161, v71
	v_med3_f32 v69, v69, s15, v209
	v_cvt_pk_fp8_f32 v158, v68, v69
	v_mov_b32_e32 v159, v1
	v_pk_mul_f32 v[156:157], v[156:157], v[160:161]
	v_pk_mul_f32 v[12:13], v[132:133], v[12:13] op_sel_hi:[0,1]
	v_pk_mul_f32 v[80:81], v[80:81], v[156:157]
	v_mov_b32_e32 v156, v137
	v_pk_mul_f32 v[68:69], v[156:157], v[154:155] op_sel_hi:[0,1]
	v_med3_f32 v71, v80, s15, v209
	v_med3_f32 v80, v81, s15, v209
	v_pk_fma_f32 v[68:69], v[68:69], v[180:181], v[96:97] neg_lo:[1,0,0] neg_hi:[1,0,0]
	v_cvt_pk_fp8_f32 v158, v71, v80 op_sel:[0,0,1]
	v_exp_f32_e32 v71, v68
	v_pk_mul_f32 v[80:81], v[156:157], v[148:149] op_sel_hi:[0,1]
	v_pk_mul_f32 v[148:149], v[156:157], v[150:151] op_sel_hi:[0,1]
	v_pk_fma_f32 v[80:81], v[80:81], v[184:185], v[182:183] neg_lo:[1,0,0] neg_hi:[1,0,0]
	v_add_f32_e32 v71, 1.0, v71
	v_rcp_f32_e32 v150, v71
	v_exp_f32_e32 v71, v69
	v_pk_mul_f32 v[104:105], v[156:157], v[152:153] op_sel_hi:[0,1]
	v_pk_fma_f32 v[104:105], v[104:105], v[78:79], v[74:75] neg_lo:[1,0,0] neg_hi:[1,0,0]
	v_pk_fma_f32 v[148:149], v[148:149], v[76:77], v[72:73] neg_lo:[1,0,0] neg_hi:[1,0,0]
	v_add_f32_e32 v71, 1.0, v71
	v_rcp_f32_e32 v151, v71
	v_exp_f32_e32 v71, v80
	v_pk_mul_f32 v[38:39], v[156:157], v[38:39] op_sel_hi:[0,1]
	v_pk_mul_f32 v[40:41], v[156:157], v[40:41] op_sel_hi:[0,1]
	v_pk_mul_f32 v[68:69], v[68:69], v[150:151]
	v_add_f32_e32 v71, 1.0, v71
	v_rcp_f32_e32 v152, v71
	v_exp_f32_e32 v71, v81
	v_pk_mul_f32 v[68:69], v[104:105], v[68:69]
	v_pk_mul_f32 v[104:105], v[134:135], v[140:141] op_sel_hi:[0,1]
	v_med3_f32 v68, v68, s15, v209
	v_add_f32_e32 v71, 1.0, v71
	v_rcp_f32_e32 v153, v71
	v_med3_f32 v69, v69, s15, v209
	v_pk_mul_f32 v[140:141], v[134:135], v[144:145] op_sel_hi:[0,1]
	v_pk_fma_f32 v[104:105], v[104:105], v[184:185], v[182:183] neg_lo:[1,0,0] neg_hi:[1,0,0]
	v_pk_mul_f32 v[80:81], v[80:81], v[152:153]
	v_pk_fma_f32 v[140:141], v[140:141], v[78:79], v[74:75] neg_lo:[1,0,0] neg_hi:[1,0,0]
	v_pk_mul_f32 v[80:81], v[148:149], v[80:81]
	v_mov_b32_e32 v148, v1
	v_cvt_pk_fp8_f32 v148, v68, v69
	v_med3_f32 v71, v80, s15, v209
	v_med3_f32 v80, v81, s15, v209
	v_pk_mul_f32 v[34:35], v[156:157], v[34:35] op_sel_hi:[0,1]
	v_cvt_pk_fp8_f32 v148, v71, v80 op_sel:[0,0,1]
	v_pk_mul_f32 v[80:81], v[134:135], v[146:147] op_sel_hi:[0,1]
	v_pk_fma_f32 v[80:81], v[80:81], v[180:181], v[96:97] neg_lo:[1,0,0] neg_hi:[1,0,0]
	v_mov_b32_e32 v149, v1
	v_exp_f32_e32 v71, v80
	v_pk_mul_f32 v[36:37], v[156:157], v[36:37] op_sel_hi:[0,1]
	v_cvt_f32_i32_e32 v5, v5
	v_cvt_f32_i32_e32 v4, v4
	v_add_f32_e32 v71, 1.0, v71
	v_rcp_f32_e32 v144, v71
	v_exp_f32_e32 v71, v81
	v_cvt_f32_i32_e32 v7, v7
	v_cvt_f32_i32_e32 v6, v6
	v_cvt_f32_i32_e32 v9, v9
	v_add_f32_e32 v71, 1.0, v71
	v_rcp_f32_e32 v145, v71
	v_exp_f32_e32 v71, v104
	v_cvt_f32_i32_e32 v8, v8
	s_movk_i32 s14, 0x1000
	v_pk_mul_f32 v[80:81], v[80:81], v[144:145]
	v_add_f32_e32 v71, 1.0, v71
	v_rcp_f32_e32 v146, v71
	v_exp_f32_e32 v71, v105
	v_pk_mul_f32 v[80:81], v[140:141], v[80:81]
	v_mov_b32_e32 v140, v1
	v_mov_b32_e32 v141, v1
	v_add_f32_e32 v71, 1.0, v71
	v_rcp_f32_e32 v147, v71
	v_med3_f32 v71, v80, s15, v209
	v_med3_f32 v80, v81, s15, v209
	v_cvt_pk_fp8_f32 v140, v71, v80
	v_pk_mul_f32 v[104:105], v[104:105], v[146:147]
	v_lshl_add_u64 v[68:69], v[66:67], 0, s[18:19]
	v_pk_mul_f32 v[104:105], v[142:143], v[104:105]
	s_nop 0
	v_med3_f32 v81, v104, s15, v209
	v_med3_f32 v83, v105, s15, v209
	v_mov_b32_e32 v104, v135
	v_cvt_pk_fp8_f32 v140, v81, v83 op_sel:[0,0,1]
	v_pk_mul_f32 v[80:81], v[104:105], v[128:129] op_sel_hi:[0,1]
	v_pk_fma_f32 v[80:81], v[80:81], v[180:181], v[96:97] neg_lo:[1,0,0] neg_hi:[1,0,0]
	v_pk_mul_f32 v[122:123], v[104:105], v[122:123] op_sel_hi:[0,1]
	v_exp_f32_e32 v71, v80
	v_pk_fma_f32 v[122:123], v[122:123], v[184:185], v[182:183] neg_lo:[1,0,0] neg_hi:[1,0,0]
	v_pk_mul_f32 v[126:127], v[104:105], v[126:127] op_sel_hi:[0,1]
	v_pk_mul_f32 v[124:125], v[104:105], v[124:125] op_sel_hi:[0,1]
	v_add_f32_e32 v71, 1.0, v71
	v_rcp_f32_e32 v128, v71
	v_exp_f32_e32 v71, v81
	v_pk_fma_f32 v[124:125], v[124:125], v[76:77], v[72:73] neg_lo:[1,0,0] neg_hi:[1,0,0]
	v_pk_fma_f32 v[126:127], v[126:127], v[78:79], v[74:75] neg_lo:[1,0,0] neg_hi:[1,0,0]
	v_pk_mul_f32 v[22:23], v[104:105], v[22:23] op_sel_hi:[0,1]
	v_add_f32_e32 v71, 1.0, v71
	v_rcp_f32_e32 v129, v71
	v_exp_f32_e32 v71, v122
	v_pk_mul_f32 v[24:25], v[104:105], v[24:25] op_sel_hi:[0,1]
	v_pk_mul_f32 v[18:19], v[104:105], v[18:19] op_sel_hi:[0,1]
	v_pk_mul_f32 v[80:81], v[80:81], v[128:129]
	v_add_f32_e32 v71, 1.0, v71
	v_rcp_f32_e32 v142, v71
	v_exp_f32_e32 v71, v123
	v_pk_mul_f32 v[80:81], v[126:127], v[80:81]
	v_pk_mul_f32 v[20:21], v[104:105], v[20:21] op_sel_hi:[0,1]
	v_mov_b32_e32 v105, 0
	v_add_f32_e32 v71, 1.0, v71
	v_rcp_f32_e32 v143, v71
	v_med3_f32 v71, v80, s15, v209
	v_med3_f32 v80, v81, s15, v209
	v_pk_mul_f32 v[122:123], v[122:123], v[142:143]
	s_nop 0
	v_pk_mul_f32 v[122:123], v[124:125], v[122:123]
	s_nop 0
	v_med3_f32 v81, v122, s15, v209
	v_mov_b32_e32 v122, v1
	v_cvt_pk_fp8_f32 v122, v71, v80
	v_med3_f32 v83, v123, s15, v209
	v_mov_b32_e32 v123, v1
	v_cvt_pk_fp8_f32 v122, v81, v83 op_sel:[0,0,1]
	v_pk_mul_f32 v[80:81], v[132:133], v[120:121] op_sel_hi:[0,1]
	v_pk_fma_f32 v[80:81], v[80:81], v[180:181], v[96:97] neg_lo:[1,0,0] neg_hi:[1,0,0]
	s_nop 0
	v_exp_f32_e32 v71, v80
	s_nop 0
	v_add_f32_e32 v71, 1.0, v71
	v_rcp_f32_e32 v120, v71
	v_exp_f32_e32 v71, v81
	s_nop 0
	v_add_f32_e32 v71, 1.0, v71
	v_rcp_f32_e32 v121, v71
	v_exp_f32_e32 v71, v114
	v_pk_mul_f32 v[80:81], v[80:81], v[120:121]
	v_add_f32_e32 v71, 1.0, v71
	v_rcp_f32_e32 v124, v71
	v_exp_f32_e32 v71, v115
	v_pk_mul_f32 v[80:81], v[118:119], v[80:81]
	v_add_f32_e32 v71, 1.0, v71
	v_rcp_f32_e32 v125, v71
	v_med3_f32 v71, v80, s15, v209
	v_med3_f32 v80, v81, s15, v209
	v_pk_mul_f32 v[114:115], v[114:115], v[124:125]
	s_nop 0
	v_pk_mul_f32 v[114:115], v[116:117], v[114:115]
	s_nop 0
	v_med3_f32 v81, v114, s15, v209
	v_mov_b32_e32 v114, v1
	v_cvt_pk_fp8_f32 v114, v71, v80
	v_mov_b32_e32 v80, v133
	v_pk_mul_f32 v[112:113], v[80:81], v[112:113] op_sel_hi:[0,1]
	v_pk_fma_f32 v[96:97], v[112:113], v[180:181], v[96:97] neg_lo:[1,0,0] neg_hi:[1,0,0]
	v_pk_mul_f32 v[106:107], v[80:81], v[106:107] op_sel_hi:[0,1]
	v_exp_f32_e32 v71, v96
	v_pk_fma_f32 v[106:107], v[106:107], v[184:185], v[182:183] neg_lo:[1,0,0] neg_hi:[1,0,0]
	v_pk_mul_f32 v[110:111], v[80:81], v[110:111] op_sel_hi:[0,1]
	v_pk_mul_f32 v[108:109], v[80:81], v[108:109] op_sel_hi:[0,1]
	v_add_f32_e32 v71, 1.0, v71
	v_rcp_f32_e32 v112, v71
	v_exp_f32_e32 v71, v97
	v_pk_fma_f32 v[72:73], v[108:109], v[76:77], v[72:73] neg_lo:[1,0,0] neg_hi:[1,0,0]
	v_pk_fma_f32 v[74:75], v[110:111], v[78:79], v[74:75] neg_lo:[1,0,0] neg_hi:[1,0,0]
	v_med3_f32 v83, v115, s15, v209
	v_add_f32_e32 v71, 1.0, v71
	v_rcp_f32_e32 v113, v71
	v_exp_f32_e32 v71, v106
	v_cvt_pk_fp8_f32 v114, v81, v83 op_sel:[0,0,1]
	v_mov_b32_e32 v83, v1
	v_pk_mul_f32 v[78:79], v[96:97], v[112:113]
	v_add_f32_e32 v71, 1.0, v71
	v_rcp_f32_e32 v116, v71
	v_exp_f32_e32 v71, v107
	v_pk_mul_f32 v[74:75], v[74:75], v[78:79]
	v_mov_b32_e32 v115, v1
	v_pk_mul_f32 v[2:3], v[80:81], v[2:3] op_sel_hi:[0,1]
	v_add_f32_e32 v71, 1.0, v71
	v_rcp_f32_e32 v117, v71
	v_med3_f32 v71, v74, s15, v209
	v_med3_f32 v74, v75, s15, v209
	v_pk_mul_f32 v[4:5], v[80:81], v[4:5] op_sel_hi:[0,1]
	v_pk_mul_f32 v[76:77], v[106:107], v[116:117]
	v_pk_mul_f32 v[6:7], v[80:81], v[6:7] op_sel_hi:[0,1]
	v_pk_mul_f32 v[72:73], v[72:73], v[76:77]
	v_pk_mul_f32 v[76:77], v[54:55], s[20:21] op_sel_hi:[1,0]
	v_med3_f32 v75, v72, s15, v209
	v_mov_b32_e32 v72, v1
	v_cvt_pk_fp8_f32 v72, v71, v74
	v_med3_f32 v73, v73, s15, v209
	v_pk_mul_f32 v[54:55], v[58:59], s[16:17] op_sel_hi:[1,0]
	v_pk_mul_f32 v[58:59], v[64:65], s[22:23] op_sel_hi:[1,0]
	v_cvt_pk_fp8_f32 v72, v75, v73 op_sel:[0,0,1]
	v_pk_mul_f32 v[74:75], v[56:57], s[20:21] op_sel_hi:[1,0]
	v_pk_mul_f32 v[56:57], v[60:61], s[16:17] op_sel_hi:[1,0]
	v_pk_mul_f32 v[60:61], v[62:63], s[22:23] op_sel_hi:[1,0]
	v_pk_mul_f32 v[62:63], v[138:139], v[102:103] op_sel_hi:[0,1]
	v_pk_fma_f32 v[62:63], v[62:63], v[54:55], v[50:51] neg_lo:[1,0,0] neg_hi:[1,0,0]
	v_pk_mul_f32 v[64:65], v[138:139], v[100:101] op_sel_hi:[0,1]
	v_exp_f32_e32 v71, v62
	v_pk_fma_f32 v[64:65], v[64:65], v[56:57], v[52:53] neg_lo:[1,0,0] neg_hi:[1,0,0]
	v_pk_fma_f32 v[98:99], v[98:99], v[60:61], v[76:77] neg_lo:[1,0,0] neg_hi:[1,0,0]
	v_pk_fma_f32 v[92:93], v[92:93], v[58:59], v[74:75] neg_lo:[1,0,0] neg_hi:[1,0,0]
	v_add_f32_e32 v71, 1.0, v71
	v_rcp_f32_e32 v78, v71
	v_exp_f32_e32 v71, v63
	v_pk_fma_f32 v[46:47], v[46:47], v[54:55], v[50:51] neg_lo:[1,0,0] neg_hi:[1,0,0]
	v_pk_fma_f32 v[48:49], v[48:49], v[56:57], v[52:53] neg_lo:[1,0,0] neg_hi:[1,0,0]
	v_pk_fma_f32 v[42:43], v[42:43], v[60:61], v[76:77] neg_lo:[1,0,0] neg_hi:[1,0,0]
	v_add_f32_e32 v71, 1.0, v71
	v_rcp_f32_e32 v79, v71
	v_exp_f32_e32 v71, v64
	v_pk_fma_f32 v[44:45], v[44:45], v[58:59], v[74:75] neg_lo:[1,0,0] neg_hi:[1,0,0]
	v_pk_fma_f32 v[38:39], v[38:39], v[54:55], v[50:51] neg_lo:[1,0,0] neg_hi:[1,0,0]
	v_pk_mul_f32 v[62:63], v[62:63], v[78:79]
	v_add_f32_e32 v71, 1.0, v71
	v_rcp_f32_e32 v96, v71
	v_exp_f32_e32 v71, v65
	v_pk_mul_f32 v[62:63], v[98:99], v[62:63]
	v_pk_fma_f32 v[40:41], v[40:41], v[56:57], v[52:53] neg_lo:[1,0,0] neg_hi:[1,0,0]
	v_med3_f32 v62, v62, s15, v209
	v_add_f32_e32 v71, 1.0, v71
	v_rcp_f32_e32 v97, v71
	v_med3_f32 v63, v63, s15, v209
	v_cvt_pk_fp8_f32 v83, v62, v63
	v_pk_mul_f32 v[62:63], v[70:71], v[90:91] op_sel_hi:[0,1]
	v_pk_mul_f32 v[64:65], v[64:65], v[96:97]
	v_pk_fma_f32 v[62:63], v[62:63], v[54:55], v[50:51] neg_lo:[1,0,0] neg_hi:[1,0,0]
	v_pk_mul_f32 v[64:65], v[92:93], v[64:65]
	v_pk_fma_f32 v[34:35], v[34:35], v[60:61], v[76:77] neg_lo:[1,0,0] neg_hi:[1,0,0]
	v_med3_f32 v64, v64, s15, v209
	v_med3_f32 v65, v65, s15, v209
	v_cvt_pk_fp8_f32 v83, v64, v65 op_sel:[0,0,1]
	v_pk_mul_f32 v[64:65], v[70:71], v[88:89] op_sel_hi:[0,1]
	v_exp_f32_e32 v71, v62
	v_pk_fma_f32 v[64:65], v[64:65], v[56:57], v[52:53] neg_lo:[1,0,0] neg_hi:[1,0,0]
	global_store_dwordx2 v0, v[82:83], s[28:29]
	v_pk_fma_f32 v[36:37], v[36:37], v[58:59], v[74:75] neg_lo:[1,0,0] neg_hi:[1,0,0]
	v_add_f32_e32 v71, 1.0, v71
	v_rcp_f32_e32 v78, v71
	v_exp_f32_e32 v71, v63
	v_pk_fma_f32 v[30:31], v[30:31], v[54:55], v[50:51] neg_lo:[1,0,0] neg_hi:[1,0,0]
	v_pk_fma_f32 v[32:33], v[32:33], v[56:57], v[52:53] neg_lo:[1,0,0] neg_hi:[1,0,0]
	v_pk_fma_f32 v[26:27], v[26:27], v[60:61], v[76:77] neg_lo:[1,0,0] neg_hi:[1,0,0]
	v_add_f32_e32 v71, 1.0, v71
	v_rcp_f32_e32 v79, v71
	v_exp_f32_e32 v71, v64
	v_pk_fma_f32 v[28:29], v[28:29], v[58:59], v[74:75] neg_lo:[1,0,0] neg_hi:[1,0,0]
	v_pk_fma_f32 v[22:23], v[22:23], v[54:55], v[50:51] neg_lo:[1,0,0] neg_hi:[1,0,0]
	v_pk_mul_f32 v[62:63], v[62:63], v[78:79]
	v_add_f32_e32 v71, 1.0, v71
	v_rcp_f32_e32 v82, v71
	v_exp_f32_e32 v71, v65
	v_pk_fma_f32 v[24:25], v[24:25], v[56:57], v[52:53] neg_lo:[1,0,0] neg_hi:[1,0,0]
	v_pk_fma_f32 v[18:19], v[18:19], v[60:61], v[76:77] neg_lo:[1,0,0] neg_hi:[1,0,0]
	v_pk_fma_f32 v[20:21], v[20:21], v[58:59], v[74:75] neg_lo:[1,0,0] neg_hi:[1,0,0]
	v_add_f32_e32 v71, 1.0, v71
	v_pk_mul_f32 v[86:87], v[70:71], v[86:87] op_sel_hi:[0,1]
	v_rcp_f32_e32 v83, v71
	v_pk_mul_f32 v[70:71], v[70:71], v[84:85] op_sel_hi:[0,1]
	v_pk_fma_f32 v[84:85], v[86:87], v[60:61], v[76:77] neg_lo:[1,0,0] neg_hi:[1,0,0]
	v_pk_fma_f32 v[70:71], v[70:71], v[58:59], v[74:75] neg_lo:[1,0,0] neg_hi:[1,0,0]
	v_pk_mul_f32 v[62:63], v[84:85], v[62:63]
	v_pk_mul_f32 v[64:65], v[64:65], v[82:83]
	v_med3_f32 v62, v62, s15, v209
	v_med3_f32 v63, v63, s15, v209
	v_cvt_pk_fp8_f32 v95, v62, v63
	v_pk_mul_f32 v[64:65], v[70:71], v[64:65]
	v_pk_fma_f32 v[14:15], v[14:15], v[54:55], v[50:51] neg_lo:[1,0,0] neg_hi:[1,0,0]
	v_med3_f32 v64, v64, s15, v209
	v_med3_f32 v65, v65, s15, v209
	v_cvt_pk_fp8_f32 v95, v64, v65 op_sel:[0,0,1]
	v_pk_fma_f32 v[16:17], v[16:17], v[56:57], v[52:53] neg_lo:[1,0,0] neg_hi:[1,0,0]
	v_pk_fma_f32 v[10:11], v[10:11], v[60:61], v[76:77] neg_lo:[1,0,0] neg_hi:[1,0,0]
	v_pk_fma_f32 v[12:13], v[12:13], v[58:59], v[74:75] neg_lo:[1,0,0] neg_hi:[1,0,0]
	global_store_dwordx2 v0, v[94:95], s[28:29] offset:2048
	v_exp_f32_e32 v0, v46
	v_pk_fma_f32 v[2:3], v[2:3], v[54:55], v[50:51] neg_lo:[1,0,0] neg_hi:[1,0,0]
	v_pk_fma_f32 v[4:5], v[4:5], v[56:57], v[52:53] neg_lo:[1,0,0] neg_hi:[1,0,0]
	v_pk_fma_f32 v[6:7], v[6:7], v[60:61], v[76:77] neg_lo:[1,0,0] neg_hi:[1,0,0]
	v_add_f32_e32 v0, 1.0, v0
	v_rcp_f32_e32 v62, v0
	v_exp_f32_e32 v0, v47
	v_mov_b32_e32 v73, v1
	v_pk_mul_f32 v[8:9], v[80:81], v[8:9] op_sel_hi:[0,1]
	v_pk_fma_f32 v[8:9], v[8:9], v[58:59], v[74:75] neg_lo:[1,0,0] neg_hi:[1,0,0]
	v_add_f32_e32 v0, 1.0, v0
	v_rcp_f32_e32 v63, v0
	v_exp_f32_e32 v0, v48
	v_mov_b32_e32 v74, 0
	v_mov_b32_e32 v56, 0
	v_pk_mul_f32 v[46:47], v[46:47], v[62:63]
	v_add_f32_e32 v0, 1.0, v0
	v_rcp_f32_e32 v64, v0
	v_exp_f32_e32 v0, v49
	v_pk_mul_f32 v[42:43], v[42:43], v[46:47]
	v_mov_b32_e32 v54, 0
	v_med3_f32 v42, v42, s15, v209
	v_add_f32_e32 v0, 1.0, v0
	v_rcp_f32_e32 v65, v0
	v_med3_f32 v43, v43, s15, v209
	v_cvt_pk_fp8_f32 v159, v42, v43
	v_add_co_u32_e32 v42, vcc, s14, v66
	v_pk_mul_f32 v[48:49], v[48:49], v[64:65]
	s_nop 0
	v_addc_co_u32_e32 v43, vcc, 0, v67, vcc
	v_pk_mul_f32 v[44:45], v[44:45], v[48:49]
	v_mov_b32_e32 v64, 0
	v_med3_f32 v0, v44, s15, v209
	v_med3_f32 v44, v45, s15, v209
	v_cvt_pk_fp8_f32 v159, v0, v44 op_sel:[0,0,1]
	v_exp_f32_e32 v0, v38
	v_mov_b32_e32 v82, 0
	v_mov_b32_e32 v78, 0
	global_store_dwordx2 v[42:43], v[158:159], off
	v_add_f32_e32 v0, 1.0, v0
	v_rcp_f32_e32 v44, v0
	v_exp_f32_e32 v0, v39
	s_nop 0
	v_add_f32_e32 v0, 1.0, v0
	v_rcp_f32_e32 v45, v0
	v_exp_f32_e32 v0, v40
	v_pk_mul_f32 v[38:39], v[38:39], v[44:45]
	v_add_f32_e32 v0, 1.0, v0
	v_rcp_f32_e32 v46, v0
	v_exp_f32_e32 v0, v41
	v_pk_mul_f32 v[34:35], v[34:35], v[38:39]
	v_add_f32_e32 v0, 1.0, v0
	v_rcp_f32_e32 v47, v0
	v_med3_f32 v34, v34, s15, v209
	v_med3_f32 v35, v35, s15, v209
	v_cvt_pk_fp8_f32 v149, v34, v35
	v_pk_mul_f32 v[40:41], v[40:41], v[46:47]
	s_nop 0
	v_pk_mul_f32 v[36:37], v[36:37], v[40:41]
	s_nop 0
	v_med3_f32 v0, v36, s15, v209
	v_med3_f32 v36, v37, s15, v209
	v_cvt_pk_fp8_f32 v149, v0, v36 op_sel:[0,0,1]
	v_exp_f32_e32 v0, v30
	global_store_dwordx2 v[42:43], v[148:149], off offset:2048
	v_add_f32_e32 v0, 1.0, v0
	v_rcp_f32_e32 v34, v0
	v_exp_f32_e32 v0, v31
	s_nop 0
	v_add_f32_e32 v0, 1.0, v0
	v_rcp_f32_e32 v35, v0
	v_exp_f32_e32 v0, v32
	v_pk_mul_f32 v[30:31], v[30:31], v[34:35]
	v_add_f32_e32 v0, 1.0, v0
	v_rcp_f32_e32 v36, v0
	v_exp_f32_e32 v0, v33
	v_pk_mul_f32 v[26:27], v[26:27], v[30:31]
	v_add_f32_e32 v0, 1.0, v0
	v_rcp_f32_e32 v37, v0
	v_med3_f32 v26, v26, s15, v209
	v_med3_f32 v27, v27, s15, v209
	v_cvt_pk_fp8_f32 v141, v26, v27
	v_pk_mul_f32 v[32:33], v[32:33], v[36:37]
	s_nop 0
	v_pk_mul_f32 v[28:29], v[28:29], v[32:33]
	s_nop 0
	v_med3_f32 v0, v28, s15, v209
	v_med3_f32 v28, v29, s15, v209
	v_cvt_pk_fp8_f32 v141, v0, v28 op_sel:[0,0,1]
	v_exp_f32_e32 v0, v22
	global_store_dwordx2 v[68:69], v[140:141], off
	v_add_f32_e32 v0, 1.0, v0
	v_rcp_f32_e32 v26, v0
	v_exp_f32_e32 v0, v23
	s_nop 0
	v_add_f32_e32 v0, 1.0, v0
	v_rcp_f32_e32 v27, v0
	v_exp_f32_e32 v0, v24
	v_pk_mul_f32 v[22:23], v[22:23], v[26:27]
	v_add_f32_e32 v0, 1.0, v0
	v_rcp_f32_e32 v28, v0
	v_exp_f32_e32 v0, v25
	v_pk_mul_f32 v[18:19], v[18:19], v[22:23]
	v_add_f32_e32 v0, 1.0, v0
	v_rcp_f32_e32 v29, v0
	v_med3_f32 v18, v18, s15, v209
	v_med3_f32 v19, v19, s15, v209
	v_cvt_pk_fp8_f32 v123, v18, v19
	v_pk_mul_f32 v[24:25], v[24:25], v[28:29]
	s_nop 0
	v_pk_mul_f32 v[20:21], v[20:21], v[24:25]
	s_nop 0
	v_med3_f32 v0, v20, s15, v209
	v_med3_f32 v20, v21, s15, v209
	v_cvt_pk_fp8_f32 v123, v0, v20 op_sel:[0,0,1]
	v_exp_f32_e32 v0, v14
	global_store_dwordx2 v[68:69], v[122:123], off offset:2048
	v_add_f32_e32 v0, 1.0, v0
	v_rcp_f32_e32 v18, v0
	v_exp_f32_e32 v0, v15
	s_nop 0
	v_add_f32_e32 v0, 1.0, v0
	v_rcp_f32_e32 v19, v0
	v_exp_f32_e32 v0, v16
	v_pk_mul_f32 v[14:15], v[14:15], v[18:19]
	v_add_f32_e32 v0, 1.0, v0
	v_rcp_f32_e32 v20, v0
	v_exp_f32_e32 v0, v17
	v_pk_mul_f32 v[10:11], v[10:11], v[14:15]
	v_add_f32_e32 v0, 1.0, v0
	v_rcp_f32_e32 v21, v0
	v_med3_f32 v10, v10, s15, v209
	v_med3_f32 v11, v11, s15, v209
	v_cvt_pk_fp8_f32 v115, v10, v11
	v_pk_mul_f32 v[16:17], v[16:17], v[20:21]
	v_add_co_u32_e32 v10, vcc, s14, v68
	v_pk_mul_f32 v[12:13], v[12:13], v[16:17]
	s_nop 0
	v_addc_co_u32_e32 v11, vcc, 0, v69, vcc
	v_med3_f32 v0, v12, s15, v209
	v_med3_f32 v12, v13, s15, v209
	v_cvt_pk_fp8_f32 v115, v0, v12 op_sel:[0,0,1]
	v_exp_f32_e32 v0, v2
	global_store_dwordx2 v[10:11], v[114:115], off
	v_add_f32_e32 v0, 1.0, v0
	v_rcp_f32_e32 v12, v0
	v_exp_f32_e32 v0, v3
	s_nop 0
	v_add_f32_e32 v0, 1.0, v0
	v_rcp_f32_e32 v13, v0
	v_exp_f32_e32 v0, v4
	v_pk_mul_f32 v[2:3], v[2:3], v[12:13]
	v_add_f32_e32 v0, 1.0, v0
	v_rcp_f32_e32 v14, v0
	v_exp_f32_e32 v0, v5
	v_pk_mul_f32 v[2:3], v[6:7], v[2:3]
	v_add_f32_e32 v0, 1.0, v0
	v_rcp_f32_e32 v15, v0
	v_med3_f32 v2, v2, s15, v209
	v_med3_f32 v3, v3, s15, v209
	v_cvt_pk_fp8_f32 v73, v2, v3
	v_pk_mul_f32 v[4:5], v[4:5], v[14:15]
	s_nop 0
	v_pk_mul_f32 v[4:5], v[8:9], v[4:5]
	s_nop 0
	v_med3_f32 v0, v4, s15, v209
	v_med3_f32 v4, v5, s15, v209
	v_cvt_pk_fp8_f32 v73, v0, v4 op_sel:[0,0,1]
	v_mov_b32_e32 v0, 0
	global_store_dwordx2 v[10:11], v[72:73], off offset:2048

; #define TIDX(wv) (opaque_s(wv) * 64 + lane_now())
; __device__ __forceinline__ int opaque_v(int v) { asm volatile("" : "+v"(v)); return v; }
; #define PG8_STAGE(bufoff, gbase, unused) do { _Pragma("unroll") for (int _i = 0; _i < 2; ++_i) \
;         __builtin_amdgcn_global_load_lds((const unsigned*)((const char*)(gbase) + voff + _i * 8192), (LAS unsigned*)(lds + (bufoff) + ldsw + _i * 8192), 16, 0, 0); } while (0)
; #define PG8_WAIT_V(n) asm volatile("s_waitcnt vmcnt(" #n ")" ::: "memory")
; #define PG8_BAR __builtin_amdgcn_s_barrier()
; template <class Epi, class Sched, bool ALIGN_EPI, bool SP2, int MODE  >
; __device__ __forceinline__ void gemm_phase(LAS unsigned char* lds, const Gemm g, const Sched S, const Epi E, unsigned long long& probe_acc, int epi_id, int wv) {
;     ...
;     const int tid = opaque_v(TIDX(wv)), wid = __builtin_amdgcn_readfirstlane(tid >> 6), lane = tid & 63, wr = wid >> 2, wc = wid & 3, fr = lane & 15, fq = lane >> 4;
;     constexpr bool FP8 = (MODE == 1); constexpr bool I8 = (MODE == 2);
;     constexpr int KTW = (FP8 || I8) ? 2 * BK : BK;
;     const int K = g.K, nt = K / KTW;
;     const unsigned voff = (unsigned)tid * 16u;
;     const size_t kstep = (size_t)HTB;
;     const size_t hA = (size_t)g.akt * HTB, tA = 2 * hA;
;     const size_t hB = (size_t)(K / KTW) * HTB, tB = 2 * hB;
;     const unsigned ldsw = (unsigned)wid * 1024u;
;     const int lane8 = (fq >> 1) * 1024 + ((fr * 64 + (fq & 1) * 32) ^ ((fr >> 3) << 5));
;     const int aoff = FP8 ? (wr * 4) * 2048 + lane8 : lds_byte(wr * 64 + fr, fq * 8), boff = FP8 ? (wc * 2) * 2048 + lane8 : lds_byte(wc * 32 + fr, fq * 8);
;     ...
;     if constexpr (SP2) {
;         PG8_STAGE(PG8_SB(0, 0), cB, voffB); PG8_STAGE(PG8_SB(0, 1), cB + hB, voffB); PG8_STAGE(PG8_SA(0, 0), cA, voffA); PG8_STAGE(PG8_SA(0, 1), cA + hA, voffA);
;         if (wr == 1) PG8_BAR;
;         PG8_WAIT_V(2); PG8_BAR;
;         PG8_STAGE(PG8_SB(1, 0), cB + kstep, voffB); PG8_STAGE(PG8_SA(1, 0), cA + kstep, voffA); PG8_STAGE(PG8_SB(1, 1), cB + hB + kstep, voffB);
;         PG8_WAIT_V(6); PG8_BAR;
.LBB0_904:
	v_and_b32_e32 v155, 15, v6
	v_bfe_u32 v190, v6, 4, 2
	v_lshlrev_b32_e32 v7, 5, v6
	v_lshlrev_b32_e32 v9, 1, v6
	v_lshlrev_b32_e32 v6, 2, v6
	v_lshlrev_b32_e32 v8, 6, v155
	v_and_b32_e32 v9, 32, v9
	v_and_b32_e32 v6, 32, v6
	v_readlane_b32 s34, v255, 6
	v_bitop3_b32 v6, v9, v6, v8 bitop3:0x36
	s_movk_i32 s1, 0x400
	s_add_i32 s89, s34, 0x18000
	s_and_b32 s9, s2, 3
	v_and_or_b32 v6, v7, s1, v6
	s_add_i32 s92, s89, s0
	v_lshl_or_b32 v8, s3, 13, v6
	v_lshrrev_b32_e32 v193, 3, v155
	v_lshlrev_b32_e32 v193, 4, v193
	v_xor_b32_e32 v8, v8, v193
	v_lshl_or_b32 v191, s9, 12, v6
	v_lshrrev_b32_e32 v154, 3, v155
	v_lshlrev_b32_e32 v154, 4, v154
	v_xor_b32_e32 v191, v191, v154
	v_lshl_add_u64 v[6:7], v[2:3], 0, s[76:77]
	s_mov_b32 m0, s92
	s_add_i32 s93, s92, 0x2000
	s_waitcnt vmcnt(2)
	s_barrier
	global_load_lds_dwordx4 v[6:7], off
	v_lshl_add_u64 v[6:7], v[2:3], 0, s[78:79]
	s_mov_b32 m0, s93
	s_add_i32 s94, s41, 0x8000
	global_load_lds_dwordx4 v[6:7], off
	v_lshl_add_u64 v[6:7], v[4:5], 0, s[76:77]
	s_mov_b32 m0, s94
	s_add_i32 s95, s41, 0xa000
	s_add_i32 s29, s34, 0x1c000
	global_load_lds_dwordx4 v[6:7], off
	v_lshl_add_u64 v[4:5], v[4:5], 0, s[78:79]
	s_mov_b32 m0, s95
	s_add_i32 s0, s29, s0
	global_load_lds_dwordx4 v[4:5], off
	v_lshl_add_u64 v[4:5], v[2:3], 0, s[44:45]
	s_mov_b32 m0, s0
	s_add_i32 s1, s0, 0x2000
	global_load_lds_dwordx4 v[4:5], off
	v_lshl_add_u64 v[2:3], v[2:3], 0, s[56:57]
	s_mov_b32 m0, s1
	s_cmpk_lt_u32 s8, 0x100
	global_load_lds_dwordx4 v[2:3], off
	s_cselect_b64 s[10:11], -1, 0
	v_writelane_b32 v255, s10, 1
	s_bfe_u32 s8, s8, 0x10006
	s_bfe_u32 s64, s2, 0x10001
	v_writelane_b32 v255, s11, 2
	s_lshl_b32 s10, s3, 6
	v_writelane_b32 v255, s10, 50
	s_lshl_b32 s10, s9, 5
	v_writelane_b32 v255, s10, 30
	s_lshl_b32 s10, s3, 2
	s_or_b32 s10, s10, s9
	s_ashr_i32 s11, s10, 31
	s_lshl_b64 s[58:59], s[10:11], 14
	s_lshl_b32 s11, s3, 3
	s_or_b32 s13, s8, s11
	s_lshl_b32 s13, s13, 10
	s_ashr_i32 s28, s13, 31
	v_writelane_b32 v255, s46, 59
	s_add_u32 s13, s46, s13
	v_writelane_b32 v255, s13, 33
	s_waitcnt vmcnt(6)
	s_mov_b32 s65, s47
	v_readlane_b32 s13, v255, 53
	s_addc_u32 s13, s13, s28
	s_cmp_lg_u64 s[16:17], 0
	v_writelane_b32 v255, s13, 34
	s_cselect_b64 s[66:67], -1, 0
	s_lshl_b32 s8, s8, 5
	v_writelane_b32 v255, s8, 7
	s_or_b32 s8, s64, s11
	s_lshl_b32 s28, s8, 10
	s_ashr_i32 s8, s28, 31
	s_lshl_b32 s3, s3, 8
	v_writelane_b32 v255, s8, 3
	s_add_i32 s8, s34, s3
	s_add_i32 s8, s8, 0x22040
	v_writelane_b32 v254, s8, 58
	s_add_i32 s11, s34, 0x24000
	s_lshl_b32 s8, s10, 11
	s_add_i32 s13, s34, 0x20040
	s_add_i32 s8, s11, s8
	v_writelane_b32 v255, s8, 0
	s_add_i32 s8, s13, s3
	s_lshl_b32 s9, s9, 10
	s_add_i32 s8, s8, s9
	v_writelane_b32 v255, s8, 19
	s_add_i32 s8, s13, s9
	s_add_i32 s3, s8, s3
	v_writelane_b32 v255, s3, 32
	s_lshl_b32 s3, s10, 6
	v_writelane_b32 v255, s3, 44
	s_ashr_i32 s3, s2, 31
	s_lshl_b64 s[8:9], s[2:3], 14
	s_add_u32 s3, s20, s8
	v_writelane_b32 v255, s3, 41
	s_addc_u32 s3, s21, s9
	s_lshl_b32 s2, s2, 11
	v_readlane_b32 s86, v254, 55
	v_writelane_b32 v255, s3, 43
	s_add_i32 s2, s11, s2
	v_readlane_b32 s87, v254, 56
	s_mov_b32 s63, s13
	s_mov_b32 s37, 0
	v_add_u32_e32 v192, s34, v8
	v_writelane_b32 v255, s2, 47
	v_readlane_b32 s87, v254, 38
	s_mov_b64 s[68:69], s[4:5]
	s_barrier
	s_branch .LBB0_907

; #define PG8_STAGE(bufoff, gbase, unused) do { _Pragma("unroll") for (int _i = 0; _i < 2; ++_i) \
;         __builtin_amdgcn_global_load_lds((const unsigned*)((const char*)(gbase) + voff + _i * 8192), (LAS unsigned*)(lds + (bufoff) + ldsw + _i * 8192), 16, 0, 0); } while (0)
; #define PG8_LDA(dst, b, h) do { _Pragma("unroll") for (int m = 0; m < 4; ++m) _Pragma("unroll") for (int k = 0; k < 2; ++k) dst[m][k] = *(const LAS bf16x8*)(lds + PG8_SA(b, h) + aoff + m * 2048 + (FP8 ? k * 16 : k * 1024)); } while (0)
; #define PG8_LDB(dst, b, h) do { _Pragma("unroll") for (int n = 0; n < 2; ++n) _Pragma("unroll") for (int k = 0; k < 2; ++k) dst[n][k] = *(const LAS bf16x8*)(lds + PG8_SB(b, h) + boff + n * 2048 + (FP8 ? k * 16 : k * 1024)); } while (0)
; #define PG8_WAIT_V(n) asm volatile("s_waitcnt vmcnt(" #n ")" ::: "memory")
; #define PG8_WAIT_L(n) asm volatile("s_waitcnt lgkmcnt(" #n ")" ::: "memory")
; #define PG8_BAR __builtin_amdgcn_s_barrier()
; #define PG8_SCHED __builtin_amdgcn_sched_barrier(0)
; template <class Epi, class Sched, bool ALIGN_EPI, bool SP2, int MODE  >
; __device__ __forceinline__ void gemm_phase(LAS unsigned char* lds, const Gemm g, const Sched S, const Epi E, unsigned long long& probe_acc, int epi_id, int wv) {
;     ...
;     f32x4 acc[2][2][4][2];
; #pragma unroll
;     for (int a = 0; a < 2; ++a)
; #pragma unroll
;         for (int b = 0; b < 2; ++b)
; #pragma unroll
;             for (int m = 0; m < 4; ++m)
; #pragma unroll
;                 for (int n = 0; n < 2; ++n) acc[a][b][m][n] = (f32x4){0.f, 0.f, 0.f, 0.f};
;     ...
;         for (int t = 0; t < nt; t += 2) {
;             const bool last = (t == nt - 2);
;             const char* a1 = cA + (size_t)(t + 1) * kstep;
;             const char* a2 = last ? nA : cA + (size_t)(t + 2) * kstep; const char* b2 = last ? nB : cB + (size_t)(t + 2) * kstep;
;             const char* a3 = a2 + kstep; const char* b3 = b2 + kstep;
;             if constexpr (SP2) {
;             PG8_LDB(B0, 0, 0); PG8_LDB(B1, 0, 1); PG8_SCHED; PG8_LDA(At, 0, 0); PG8_STAGE(PG8_SA(1, 1), a1 + hA, voffA);
;             PG8_WAIT_V(8); PG8_WAIT_L(0); PG8_BAR; PG8_MMA(0, 0, At, B0); PG8_MMA(0, 1, At, B1); PG8_BAR; PG8_SCHED;
.LBB0_913:
	s_add_u32 s8, s4, s12
	s_addc_u32 s9, s5, 0
	s_add_u32 s34, s6, 0x8000
	v_mov_b32_e32 v2, 0
	s_waitcnt vmcnt(0)
	v_lshl_add_u64 v[130:131], s[8:9], 0, v[0:1]
	s_addc_u32 s35, s7, 0
	s_mov_b32 s46, -2
	s_mov_b64 s[6:7], 0
	s_waitcnt lgkmcnt(0)
	v_mov_b32_e32 v3, v2
	v_mov_b32_e32 v4, v2
	v_mov_b32_e32 v5, v2
	v_mov_b32_e32 v6, v2
	v_mov_b32_e32 v7, v2
	v_mov_b32_e32 v8, v2
	v_mov_b32_e32 v9, v2
	v_mov_b32_e32 v10, v2
	v_mov_b32_e32 v11, v2
	v_mov_b32_e32 v12, v2
	v_mov_b32_e32 v13, v2
	v_mov_b32_e32 v14, v2
	v_mov_b32_e32 v15, v2
	v_mov_b32_e32 v16, v2
	v_mov_b32_e32 v17, v2
	v_mov_b32_e32 v18, v2
	v_mov_b32_e32 v19, v2
	v_mov_b32_e32 v20, v2
	v_mov_b32_e32 v21, v2
	v_mov_b32_e32 v22, v2
	v_mov_b32_e32 v23, v2
	v_mov_b32_e32 v24, v2
	v_mov_b32_e32 v25, v2
	v_mov_b32_e32 v26, v2
	v_mov_b32_e32 v27, v2
	v_mov_b32_e32 v28, v2
	v_mov_b32_e32 v29, v2
	v_mov_b32_e32 v30, v2
	v_mov_b32_e32 v31, v2
	v_mov_b32_e32 v32, v2
	v_mov_b32_e32 v33, v2
	v_mov_b32_e32 v66, v2
	v_mov_b32_e32 v67, v2
	v_mov_b32_e32 v68, v2
	v_mov_b32_e32 v69, v2
	v_mov_b32_e32 v70, v2
	v_mov_b32_e32 v71, v2
	v_mov_b32_e32 v72, v2
	v_mov_b32_e32 v73, v2
	v_mov_b32_e32 v74, v2
	v_mov_b32_e32 v75, v2
	v_mov_b32_e32 v76, v2
	v_mov_b32_e32 v77, v2
	v_mov_b32_e32 v78, v2
	v_mov_b32_e32 v79, v2
	v_mov_b32_e32 v80, v2
	v_mov_b32_e32 v81, v2
	v_mov_b32_e32 v82, v2
	v_mov_b32_e32 v83, v2
	v_mov_b32_e32 v84, v2
	v_mov_b32_e32 v85, v2
	v_mov_b32_e32 v86, v2
	v_mov_b32_e32 v87, v2
	v_mov_b32_e32 v88, v2
	v_mov_b32_e32 v89, v2
	v_mov_b32_e32 v90, v2
	v_mov_b32_e32 v91, v2
	v_mov_b32_e32 v92, v2
	v_mov_b32_e32 v93, v2
	v_mov_b32_e32 v94, v2
	v_mov_b32_e32 v95, v2
	v_mov_b32_e32 v96, v2
	v_mov_b32_e32 v97, v2
	v_mov_b32_e32 v34, v2
	v_mov_b32_e32 v35, v2
	v_mov_b32_e32 v36, v2
	v_mov_b32_e32 v37, v2
	v_mov_b32_e32 v38, v2
	v_mov_b32_e32 v39, v2
	v_mov_b32_e32 v40, v2
	v_mov_b32_e32 v41, v2
	v_mov_b32_e32 v42, v2
	v_mov_b32_e32 v43, v2
	v_mov_b32_e32 v44, v2
	v_mov_b32_e32 v45, v2
	v_mov_b32_e32 v46, v2
	v_mov_b32_e32 v47, v2
	v_mov_b32_e32 v48, v2
	v_mov_b32_e32 v49, v2
	v_mov_b32_e32 v50, v2
	v_mov_b32_e32 v51, v2
	v_mov_b32_e32 v52, v2
	v_mov_b32_e32 v53, v2
	v_mov_b32_e32 v54, v2
	v_mov_b32_e32 v55, v2
	v_mov_b32_e32 v56, v2
	v_mov_b32_e32 v57, v2
	v_mov_b32_e32 v58, v2
	v_mov_b32_e32 v59, v2
	v_mov_b32_e32 v60, v2
	v_mov_b32_e32 v61, v2
	v_mov_b32_e32 v62, v2
	v_mov_b32_e32 v63, v2
	v_mov_b32_e32 v64, v2
	v_mov_b32_e32 v65, v2
	v_mov_b32_e32 v98, v2
	v_mov_b32_e32 v99, v2
	v_mov_b32_e32 v100, v2
	v_mov_b32_e32 v101, v2
	v_mov_b32_e32 v102, v2
	v_mov_b32_e32 v103, v2
	v_mov_b32_e32 v104, v2
	v_mov_b32_e32 v105, v2
	v_mov_b32_e32 v106, v2
	v_mov_b32_e32 v107, v2
	v_mov_b32_e32 v108, v2
	v_mov_b32_e32 v109, v2
	v_mov_b32_e32 v110, v2
	v_mov_b32_e32 v111, v2
	v_mov_b32_e32 v112, v2
	v_mov_b32_e32 v113, v2
	v_mov_b32_e32 v114, v2
	v_mov_b32_e32 v115, v2
	v_mov_b32_e32 v116, v2
	v_mov_b32_e32 v117, v2
	v_mov_b32_e32 v118, v2
	v_mov_b32_e32 v119, v2
	v_mov_b32_e32 v120, v2
	v_mov_b32_e32 v121, v2
	v_mov_b32_e32 v122, v2
	v_mov_b32_e32 v123, v2
	v_mov_b32_e32 v124, v2
	v_mov_b32_e32 v125, v2
	v_mov_b32_e32 v126, v2
	v_mov_b32_e32 v127, v2
	v_mov_b32_e32 v128, v2
	v_mov_b32_e32 v129, v2
	s_mov_b64 s[42:43], 0xb0000
	v_xor_b32_e32 v193, 16, v192
.LBB0_914:
	v_add_u32_e32 v144, s14, v191
	v_add_u32_e32 v148, s27, v191
	s_add_u32 s8, s4, s6
	ds_read_b128 v[132:135], v144
	v_xor_b32_e32 v154, 16, v144
	ds_read_b128 v[136:139], v154
	ds_read_b128 v[140:143], v144 offset:2048
	ds_read_b128 v[144:147], v154 offset:2048
	ds_read_b128 v[156:159], v148
	v_xor_b32_e32 v154, 16, v148
	ds_read_b128 v[160:163], v154
	ds_read_b128 v[164:167], v148 offset:2048
	ds_read_b128 v[168:171], v154 offset:2048
	s_addc_u32 s9, s5, s7
	s_add_u32 s8, s8, 0x8000
	s_addc_u32 s9, s9, 0
	s_add_u32 s10, s34, s6
	s_addc_u32 s11, s35, s7
	s_cmp_eq_u32 s6, 0xa8000
	s_cselect_b32 s9, s69, s9
	s_cselect_b32 s8, s68, s8
	s_cselect_b32 s11, s91, s11
	s_cselect_b32 s10, s90, s10
	v_lshl_add_u64 v[148:149], v[130:131], 0, s[6:7]
	v_lshl_add_u64 v[150:151], v[148:149], 0, s[76:77]
	s_add_i32 m0, s41, 0xc000
	ds_read_b128 v[172:175], v192
	ds_read_b128 v[176:179], v193
	ds_read_b128 v[180:183], v192 offset:2048
	ds_read_b128 v[184:187], v193 offset:2048
	ds_read_b128 v[212:215], v192 offset:4096
	ds_read_b128 v[216:219], v193 offset:4096
	ds_read_b128 v[220:223], v192 offset:6144
	ds_read_b128 v[224:227], v193 offset:6144
	global_load_lds_dwordx4 v[150:151], off
	v_lshl_add_u64 v[148:149], v[148:149], 0, s[78:79]
	s_add_i32 m0, s41, 0xe000
	s_nop 0
	global_load_lds_dwordx4 v[148:149], off
	s_waitcnt vmcnt(8)
	s_waitcnt lgkmcnt(0)
	s_barrier
	s_setprio 1
	s_waitcnt lgkmcnt(0)
	v_mfma_scale_f32_16x16x128_f8f6f4 v[126:129], v[132:139], v[172:179], v[126:129], v208, v208 op_sel_hi:[0,0,0]
	v_mfma_scale_f32_16x16x128_f8f6f4 v[122:125], v[140:147], v[172:179], v[122:125], v208, v208 op_sel_hi:[0,0,0]
	v_mfma_scale_f32_16x16x128_f8f6f4 v[118:121], v[132:139], v[180:187], v[118:121], v208, v208 op_sel_hi:[0,0,0]
	v_mfma_scale_f32_16x16x128_f8f6f4 v[114:117], v[140:147], v[180:187], v[114:117], v208, v208 op_sel_hi:[0,0,0]
	v_mfma_scale_f32_16x16x128_f8f6f4 v[110:113], v[132:139], v[212:219], v[110:113], v208, v208 op_sel_hi:[0,0,0]
	v_mfma_scale_f32_16x16x128_f8f6f4 v[106:109], v[140:147], v[212:219], v[106:109], v208, v208 op_sel_hi:[0,0,0]
	v_mfma_scale_f32_16x16x128_f8f6f4 v[102:105], v[132:139], v[220:227], v[102:105], v208, v208 op_sel_hi:[0,0,0]
	v_mfma_scale_f32_16x16x128_f8f6f4 v[98:101], v[140:147], v[220:227], v[98:101], v208, v208 op_sel_hi:[0,0,0]
	s_setprio 0
	s_setprio 1
	v_mfma_scale_f32_16x16x128_f8f6f4 v[148:151], v[156:163], v[172:179], v[62:65], v208, v208 op_sel_hi:[0,0,0]
	v_mfma_scale_f32_16x16x128_f8f6f4 v[172:175], v[164:171], v[172:179], v[58:61], v208, v208 op_sel_hi:[0,0,0]
	v_mfma_scale_f32_16x16x128_f8f6f4 v[176:179], v[156:163], v[180:187], v[54:57], v208, v208 op_sel_hi:[0,0,0]
	v_mfma_scale_f32_16x16x128_f8f6f4 v[180:183], v[164:171], v[180:187], v[50:53], v208, v208 op_sel_hi:[0,0,0]
	v_mfma_scale_f32_16x16x128_f8f6f4 v[184:187], v[156:163], v[212:219], v[46:49], v208, v208 op_sel_hi:[0,0,0]
	v_mfma_scale_f32_16x16x128_f8f6f4 v[194:197], v[164:171], v[212:219], v[42:45], v208, v208 op_sel_hi:[0,0,0]
	v_mfma_scale_f32_16x16x128_f8f6f4 v[200:203], v[156:163], v[220:227], v[38:41], v208, v208 op_sel_hi:[0,0,0]
	v_mfma_scale_f32_16x16x128_f8f6f4 v[212:215], v[164:171], v[220:227], v[34:37], v208, v208 op_sel_hi:[0,0,0]
	s_setprio 0
	s_barrier
; #define PG8_STAGE(bufoff, gbase, unused) do { _Pragma("unroll") for (int _i = 0; _i < 2; ++_i) \
;         __builtin_amdgcn_global_load_lds((const unsigned*)((const char*)(gbase) + voff + _i * 8192), (LAS unsigned*)(lds + (bufoff) + ldsw + _i * 8192), 16, 0, 0); } while (0)
; #define PG8_LDA(dst, b, h) do { _Pragma("unroll") for (int m = 0; m < 4; ++m) _Pragma("unroll") for (int k = 0; k < 2; ++k) dst[m][k] = *(const LAS bf16x8*)(lds + PG8_SA(b, h) + aoff + m * 2048 + (FP8 ? k * 16 : k * 1024)); } while (0)
; #define PG8_LDB(dst, b, h) do { _Pragma("unroll") for (int n = 0; n < 2; ++n) _Pragma("unroll") for (int k = 0; k < 2; ++k) dst[n][k] = *(const LAS bf16x8*)(lds + PG8_SB(b, h) + boff + n * 2048 + (FP8 ? k * 16 : k * 1024)); } while (0)
; #define PG8_WAIT_V(n) asm volatile("s_waitcnt vmcnt(" #n ")" ::: "memory")
; #define PG8_WAIT_L(n) asm volatile("s_waitcnt lgkmcnt(" #n ")" ::: "memory")
; #define PG8_BAR __builtin_amdgcn_s_barrier()
; #define PG8_SCHED __builtin_amdgcn_sched_barrier(0)
; template <class Epi, class Sched, bool ALIGN_EPI, bool SP2, int MODE  >
; __device__ __forceinline__ void gemm_phase(LAS unsigned char* lds, const Gemm g, const Sched S, const Epi E, unsigned long long& probe_acc, int epi_id, int wv) {
;     ...
;             PG8_LDB(B0, 0, 0); PG8_LDB(B1, 0, 1); PG8_SCHED; PG8_LDA(At, 0, 0); PG8_STAGE(PG8_SA(1, 1), a1 + hA, voffA);
;             PG8_WAIT_V(8); PG8_WAIT_L(0); PG8_BAR; PG8_MMA(0, 0, At, B0); PG8_MMA(0, 1, At, B1); PG8_BAR; PG8_SCHED;
;             PG8_LDA(At, 0, 1); PG8_STAGE(PG8_SB(0, 0), b2, voffB); PG8_STAGE(PG8_SB(0, 1), b2 + hB, voffB); PG8_STAGE(PG8_SA(0, 0), a2, voffA);
;             PG8_WAIT_V(8); PG8_WAIT_L(0); PG8_BAR; PG8_MMA(1, 0, At, B0); PG8_MMA(1, 1, At, B1); PG8_BAR; PG8_SCHED;
;             PG8_LDB(B0, 1, 0); PG8_LDB(B1, 1, 1); PG8_SCHED; PG8_LDA(At, 1, 0); PG8_STAGE(PG8_SA(0, 1), a2 + hA, voffA);
	s_mov_b32 m0, s15
	v_lshl_add_u64 v[152:153], s[10:11], 0, v[0:1]
	s_nop 2
	ds_read_b128 v[34:37], v192 offset:16384
	ds_read_b128 v[38:41], v193 offset:16384
	ds_read_b128 v[42:45], v192 offset:18432
	ds_read_b128 v[46:49], v193 offset:18432
	ds_read_b128 v[50:53], v192 offset:20480
	ds_read_b128 v[54:57], v193 offset:20480
	ds_read_b128 v[58:61], v192 offset:22528
	ds_read_b128 v[62:65], v193 offset:22528
	global_load_lds_dwordx4 v[152:153], off
	v_lshl_add_u64 v[188:189], v[152:153], 0, s[70:71]
	s_mov_b32 m0, s26
	s_nop 0
	global_load_lds_dwordx4 v[188:189], off
	v_lshl_add_u64 v[188:189], v[152:153], 0, s[42:43]
	s_mov_b32 m0, s39
	s_nop 0
	global_load_lds_dwordx4 v[188:189], off
	v_lshl_add_u64 v[188:189], v[152:153], 0, s[48:49]
	s_mov_b32 m0, s40
	s_nop 0
	global_load_lds_dwordx4 v[188:189], off
	v_lshl_add_u64 v[188:189], s[8:9], 0, v[0:1]
	s_mov_b32 m0, s41
	v_lshl_add_u64 v[204:205], v[188:189], 0, s[70:71]
	global_load_lds_dwordx4 v[188:189], off
	s_mov_b32 m0, s84
	s_nop 0
	global_load_lds_dwordx4 v[204:205], off
	s_waitcnt vmcnt(8)
	s_waitcnt lgkmcnt(0)
	s_barrier
	s_setprio 1
	s_waitcnt lgkmcnt(0)
	v_mfma_scale_f32_16x16x128_f8f6f4 v[94:97], v[132:139], v[34:41], v[94:97], v208, v208 op_sel_hi:[0,0,0]
	v_mfma_scale_f32_16x16x128_f8f6f4 v[90:93], v[140:147], v[34:41], v[90:93], v208, v208 op_sel_hi:[0,0,0]
	v_mfma_scale_f32_16x16x128_f8f6f4 v[86:89], v[132:139], v[42:49], v[86:89], v208, v208 op_sel_hi:[0,0,0]
	v_mfma_scale_f32_16x16x128_f8f6f4 v[82:85], v[140:147], v[42:49], v[82:85], v208, v208 op_sel_hi:[0,0,0]
	v_mfma_scale_f32_16x16x128_f8f6f4 v[78:81], v[132:139], v[50:57], v[78:81], v208, v208 op_sel_hi:[0,0,0]
	v_mfma_scale_f32_16x16x128_f8f6f4 v[74:77], v[140:147], v[50:57], v[74:77], v208, v208 op_sel_hi:[0,0,0]
	v_mfma_scale_f32_16x16x128_f8f6f4 v[216:219], v[132:139], v[58:65], v[70:73], v208, v208 op_sel_hi:[0,0,0]
	v_mfma_scale_f32_16x16x128_f8f6f4 v[220:223], v[140:147], v[58:65], v[66:69], v208, v208 op_sel_hi:[0,0,0]
	s_setprio 0
	s_setprio 1
	v_mfma_scale_f32_16x16x128_f8f6f4 v[224:227], v[156:163], v[34:41], v[30:33], v208, v208 op_sel_hi:[0,0,0]
	v_mfma_scale_f32_16x16x128_f8f6f4 v[228:231], v[164:171], v[34:41], v[26:29], v208, v208 op_sel_hi:[0,0,0]
	v_mfma_scale_f32_16x16x128_f8f6f4 v[232:235], v[156:163], v[42:49], v[22:25], v208, v208 op_sel_hi:[0,0,0]
	v_mfma_scale_f32_16x16x128_f8f6f4 v[236:239], v[164:171], v[42:49], v[18:21], v208, v208 op_sel_hi:[0,0,0]
	v_mfma_scale_f32_16x16x128_f8f6f4 v[240:243], v[156:163], v[50:57], v[14:17], v208, v208 op_sel_hi:[0,0,0]
	v_mfma_scale_f32_16x16x128_f8f6f4 v[244:247], v[164:171], v[50:57], v[10:13], v208, v208 op_sel_hi:[0,0,0]
	v_mfma_scale_f32_16x16x128_f8f6f4 v[248:251], v[156:163], v[58:65], v[6:9], v208, v208 op_sel_hi:[0,0,0]
	v_mfma_scale_f32_16x16x128_f8f6f4 v[204:207], v[164:171], v[58:65], v[2:5], v208, v208 op_sel_hi:[0,0,0]
	s_setprio 0
	s_barrier
	s_nop 1
	v_add_u32_e32 v14, s89, v191
	v_add_u32_e32 v18, s29, v191
	s_nop 0
	ds_read_b128 v[2:5], v14
	v_xor_b32_e32 v154, 16, v14
	ds_read_b128 v[6:9], v154
	ds_read_b128 v[10:13], v14 offset:2048
	ds_read_b128 v[14:17], v154 offset:2048
	ds_read_b128 v[132:135], v18
	v_xor_b32_e32 v154, 16, v18
	ds_read_b128 v[136:139], v154
	ds_read_b128 v[140:143], v18 offset:2048
	ds_read_b128 v[144:147], v154 offset:2048
	s_add_u32 s8, s8, s12
	s_addc_u32 s9, s9, 0
	s_mov_b32 m0, s85
	v_lshl_add_u64 v[42:43], s[8:9], 0, v[0:1]
	ds_read_b128 v[18:21], v192 offset:32768
	ds_read_b128 v[22:25], v193 offset:32768
	ds_read_b128 v[26:29], v192 offset:34816
	ds_read_b128 v[30:33], v193 offset:34816
	ds_read_b128 v[34:37], v192 offset:36864
	ds_read_b128 v[38:41], v193 offset:36864
	ds_read_b128 v[66:69], v192 offset:38912
	ds_read_b128 v[70:73], v193 offset:38912
	global_load_lds_dwordx4 v[42:43], off
	v_lshl_add_u64 v[42:43], v[42:43], 0, s[70:71]
	s_mov_b32 m0, s88
	s_nop 0
	global_load_lds_dwordx4 v[42:43], off
	s_waitcnt vmcnt(8)
	s_waitcnt lgkmcnt(0)
	s_barrier
; #define PG8_STAGE(bufoff, gbase, unused) do { _Pragma("unroll") for (int _i = 0; _i < 2; ++_i) \
;         __builtin_amdgcn_global_load_lds((const unsigned*)((const char*)(gbase) + voff + _i * 8192), (LAS unsigned*)(lds + (bufoff) + ldsw + _i * 8192), 16, 0, 0); } while (0)
; #define PG8_LDA(dst, b, h) do { _Pragma("unroll") for (int m = 0; m < 4; ++m) _Pragma("unroll") for (int k = 0; k < 2; ++k) dst[m][k] = *(const LAS bf16x8*)(lds + PG8_SA(b, h) + aoff + m * 2048 + (FP8 ? k * 16 : k * 1024)); } while (0)
; #define PG8_WAIT_V(n) asm volatile("s_waitcnt vmcnt(" #n ")" ::: "memory")
; #define PG8_WAIT_L(n) asm volatile("s_waitcnt lgkmcnt(" #n ")" ::: "memory")
; #define PG8_BAR __builtin_amdgcn_s_barrier()
; #define PG8_SCHED __builtin_amdgcn_sched_barrier(0)
; template <class Epi, class Sched, bool ALIGN_EPI, bool SP2, int MODE  >
; __device__ __forceinline__ void gemm_phase(LAS unsigned char* lds, const Gemm g, const Sched S, const Epi E, unsigned long long& probe_acc, int epi_id, int wv) {
;     ...
;             PG8_WAIT_V(8); PG8_WAIT_L(0); PG8_BAR; PG8_MMA(0, 0, At, B0); PG8_MMA(0, 1, At, B1); PG8_BAR; PG8_SCHED;
;             PG8_LDA(At, 1, 1); PG8_STAGE(PG8_SB(1, 0), b3, voffB); PG8_STAGE(PG8_SB(1, 1), b3 + hB, voffB); PG8_STAGE(PG8_SA(1, 0), a3, voffA);
;             PG8_WAIT_V(8); PG8_WAIT_L(0); PG8_BAR; PG8_MMA(1, 0, At, B0); PG8_MMA(1, 1, At, B1); PG8_BAR; PG8_SCHED;
;     ...
;         if constexpr (ALIGN_EPI) { if (wr == 0) PG8_BAR; }
	s_setprio 1
	s_waitcnt lgkmcnt(0)
	v_mfma_scale_f32_16x16x128_f8f6f4 v[126:129], v[2:9], v[18:25], v[126:129], v208, v208 op_sel_hi:[0,0,0]
	v_mfma_scale_f32_16x16x128_f8f6f4 v[122:125], v[10:17], v[18:25], v[122:125], v208, v208 op_sel_hi:[0,0,0]
	v_mfma_scale_f32_16x16x128_f8f6f4 v[118:121], v[2:9], v[26:33], v[118:121], v208, v208 op_sel_hi:[0,0,0]
	v_mfma_scale_f32_16x16x128_f8f6f4 v[114:117], v[10:17], v[26:33], v[114:117], v208, v208 op_sel_hi:[0,0,0]
	v_mfma_scale_f32_16x16x128_f8f6f4 v[110:113], v[2:9], v[34:41], v[110:113], v208, v208 op_sel_hi:[0,0,0]
	v_mfma_scale_f32_16x16x128_f8f6f4 v[106:109], v[10:17], v[34:41], v[106:109], v208, v208 op_sel_hi:[0,0,0]
	v_mfma_scale_f32_16x16x128_f8f6f4 v[102:105], v[2:9], v[66:73], v[102:105], v208, v208 op_sel_hi:[0,0,0]
	v_mfma_scale_f32_16x16x128_f8f6f4 v[98:101], v[10:17], v[66:73], v[98:101], v208, v208 op_sel_hi:[0,0,0]
	s_setprio 0
	s_setprio 1
	v_mfma_scale_f32_16x16x128_f8f6f4 v[62:65], v[132:139], v[18:25], v[148:151], v208, v208 op_sel_hi:[0,0,0]
	v_mfma_scale_f32_16x16x128_f8f6f4 v[58:61], v[140:147], v[18:25], v[172:175], v208, v208 op_sel_hi:[0,0,0]
	v_mfma_scale_f32_16x16x128_f8f6f4 v[54:57], v[132:139], v[26:33], v[176:179], v208, v208 op_sel_hi:[0,0,0]
	v_mfma_scale_f32_16x16x128_f8f6f4 v[50:53], v[140:147], v[26:33], v[180:183], v208, v208 op_sel_hi:[0,0,0]
	v_mfma_scale_f32_16x16x128_f8f6f4 v[46:49], v[132:139], v[34:41], v[184:187], v208, v208 op_sel_hi:[0,0,0]
	v_mfma_scale_f32_16x16x128_f8f6f4 v[42:45], v[140:147], v[34:41], v[194:197], v208, v208 op_sel_hi:[0,0,0]
	v_mfma_scale_f32_16x16x128_f8f6f4 v[38:41], v[132:139], v[66:73], v[200:203], v208, v208 op_sel_hi:[0,0,0]
	v_mfma_scale_f32_16x16x128_f8f6f4 v[34:37], v[140:147], v[66:73], v[212:215], v208, v208 op_sel_hi:[0,0,0]
	s_setprio 0
	s_barrier
	s_mov_b32 m0, s92
	v_lshl_add_u64 v[26:27], v[152:153], 0, s[76:77]
	ds_read_b128 v[18:21], v192 offset:49152
	ds_read_b128 v[22:25], v193 offset:49152
	ds_read_b128 v[156:159], v192 offset:51200
	ds_read_b128 v[160:163], v193 offset:51200
	ds_read_b128 v[164:167], v192 offset:53248
	ds_read_b128 v[168:171], v193 offset:53248
	ds_read_b128 v[172:175], v192 offset:55296
	ds_read_b128 v[176:179], v193 offset:55296
	global_load_lds_dwordx4 v[26:27], off
	v_lshl_add_u64 v[26:27], v[152:153], 0, s[78:79]
	s_mov_b32 m0, s93
	s_nop 0
	global_load_lds_dwordx4 v[26:27], off
	v_lshl_add_u64 v[26:27], v[152:153], 0, s[44:45]
	s_mov_b32 m0, s0
	s_nop 0
	global_load_lds_dwordx4 v[26:27], off
	v_lshl_add_u64 v[26:27], v[152:153], 0, s[56:57]
	s_mov_b32 m0, s1
	s_nop 0
	global_load_lds_dwordx4 v[26:27], off
	v_lshl_add_u64 v[26:27], v[188:189], 0, s[76:77]
	s_mov_b32 m0, s94
	s_nop 0
	global_load_lds_dwordx4 v[26:27], off
	v_lshl_add_u64 v[26:27], v[188:189], 0, s[78:79]
	s_mov_b32 m0, s95
	s_nop 0
	global_load_lds_dwordx4 v[26:27], off
	s_waitcnt vmcnt(8)
	s_waitcnt lgkmcnt(0)
	s_barrier
	s_setprio 1
	s_waitcnt lgkmcnt(0)
	v_mfma_scale_f32_16x16x128_f8f6f4 v[94:97], v[2:9], v[18:25], v[94:97], v208, v208 op_sel_hi:[0,0,0]
	v_mfma_scale_f32_16x16x128_f8f6f4 v[90:93], v[10:17], v[18:25], v[90:93], v208, v208 op_sel_hi:[0,0,0]
	v_mfma_scale_f32_16x16x128_f8f6f4 v[86:89], v[2:9], v[156:163], v[86:89], v208, v208 op_sel_hi:[0,0,0]
	v_mfma_scale_f32_16x16x128_f8f6f4 v[82:85], v[10:17], v[156:163], v[82:85], v208, v208 op_sel_hi:[0,0,0]
	v_mfma_scale_f32_16x16x128_f8f6f4 v[78:81], v[2:9], v[164:171], v[78:81], v208, v208 op_sel_hi:[0,0,0]
	v_mfma_scale_f32_16x16x128_f8f6f4 v[74:77], v[10:17], v[164:171], v[74:77], v208, v208 op_sel_hi:[0,0,0]
	v_mfma_scale_f32_16x16x128_f8f6f4 v[70:73], v[2:9], v[172:179], v[216:219], v208, v208 op_sel_hi:[0,0,0]
	v_mfma_scale_f32_16x16x128_f8f6f4 v[66:69], v[10:17], v[172:179], v[220:223], v208, v208 op_sel_hi:[0,0,0]
	s_setprio 0
	s_setprio 1
	v_mfma_scale_f32_16x16x128_f8f6f4 v[30:33], v[132:139], v[18:25], v[224:227], v208, v208 op_sel_hi:[0,0,0]
	v_mfma_scale_f32_16x16x128_f8f6f4 v[26:29], v[140:147], v[18:25], v[228:231], v208, v208 op_sel_hi:[0,0,0]
	v_mfma_scale_f32_16x16x128_f8f6f4 v[22:25], v[132:139], v[156:163], v[232:235], v208, v208 op_sel_hi:[0,0,0]
	v_mfma_scale_f32_16x16x128_f8f6f4 v[18:21], v[140:147], v[156:163], v[236:239], v208, v208 op_sel_hi:[0,0,0]
	v_mfma_scale_f32_16x16x128_f8f6f4 v[14:17], v[132:139], v[164:171], v[240:243], v208, v208 op_sel_hi:[0,0,0]
	v_mfma_scale_f32_16x16x128_f8f6f4 v[10:13], v[140:147], v[164:171], v[244:247], v208, v208 op_sel_hi:[0,0,0]
	v_mfma_scale_f32_16x16x128_f8f6f4 v[6:9], v[132:139], v[172:179], v[248:251], v208, v208 op_sel_hi:[0,0,0]
	v_mfma_scale_f32_16x16x128_f8f6f4 v[2:5], v[140:147], v[172:179], v[204:207], v208, v208 op_sel_hi:[0,0,0]
	s_setprio 0
	s_barrier
	s_add_i32 s46, s46, 2
	s_add_u32 s6, s6, 0x8000
	s_addc_u32 s7, s7, 0
	s_cmp_gt_u32 s46, 41
	s_cbranch_scc0 .LBB0_914
	v_readlane_b32 s4, v255, 1
	v_readlane_b32 s5, v255, 2
	s_and_b64 vcc, exec, s[4:5]
	s_cbranch_vccz .LBB0_917
	s_barrier
